# P1: workgroups 128..255 run the weight-conversion work before their in-proj GEMM unit (others after), splitting the conversion HBM traffic into two windows
# speedup vs baseline: 1.0048x; 1.0032x over previous
; #define LAS __attribute__((address_space(3)))
; __global__ void __launch_bounds__(512, 2) mk_fwd(Args a) {
;     extern __shared__ __attribute__((aligned(16))) unsigned char lds_raw[];
;     LAS unsigned char* lds = (LAS unsigned char*)lds_raw;
;     cg::grid_group grid = cg::this_grid();
;     const int G = gridDim.x;
;     if (threadIdx.x < 2) ((volatile LAS unsigned*)(lds + LDS_BARST))[threadIdx.x] = 0u;
;     __syncthreads();
;     if (a.ws == nullptr) grid.sync();
;     const XcdBarrier xbar = xcd_barrier_post((unsigned*)(a.ws + WS_BAR), (volatile LAS unsigned*)(lds + LDS_BARST));
_Z6mk_fwd4Args:
	s_load_dwordx8 s[4:11], s[0:1], 0x80
	s_load_dwordx4 s[88:91], s[0:1], 0xa0
	s_load_dword s18, s[0:1], 0xb0
	s_mov_b32 s3, 0
	v_writelane_b32 v255, s3, 54
	v_writelane_b32 v255, 0, 56
	v_writelane_b32 v253, s2, 0
	v_and_b32_e32 v236, 0x3ff, v0
	v_cmp_gt_u32_e32 vcc, 2, v236
	s_waitcnt lgkmcnt(0)
	v_writelane_b32 v253, s4, 1
	s_nop 1
	v_writelane_b32 v253, s5, 2
	v_writelane_b32 v253, s6, 3
	v_writelane_b32 v253, s7, 4
	v_writelane_b32 v253, s8, 5
	v_writelane_b32 v253, s9, 6
	v_writelane_b32 v253, s10, 7
	v_writelane_b32 v253, s11, 8
	s_add_u32 s4, s0, 0xa8
	s_addc_u32 s5, s1, 0
	s_and_saveexec_b64 s[2:3], vcc
	v_lshl_add_u32 v1, v236, 2, 0
	v_add_u32_e32 v1, 0x23fc0, v1
	v_mov_b32_e32 v2, 0
	ds_write_b32 v1, v2
	s_or_b64 exec, exec, s[2:3]
	s_cmp_lg_u64 s[88:89], 0
	s_waitcnt lgkmcnt(0)
	s_barrier
	s_cbranch_scc1 .LBB0_14
	v_lshrrev_b32_e32 v1, 20, v0
	v_lshrrev_b32_e32 v0, 10, v0
	v_or_b32_e32 v0, v0, v1
	s_movk_i32 s2, 0x3ff
	v_and_or_b32 v0, v0, s2, v236
	v_cmp_eq_u32_e32 vcc, 0, v0
	s_barrier
	s_and_saveexec_b64 s[2:3], vcc
	s_cbranch_execz .LBB0_13
	buffer_wbl2 sc1
	s_load_dwordx2 s[4:5], s[4:5], 0x58
	s_mov_b64 s[6:7], exec
	v_mbcnt_lo_u32_b32 v0, s6, 0
	v_mbcnt_hi_u32_b32 v0, s7, v0
	v_cmp_eq_u32_e32 vcc, 0, v0
	s_waitcnt lgkmcnt(0)
	s_load_dword s10, s[4:5], 0x28
	s_and_saveexec_b64 s[8:9], vcc
	s_cbranch_execz .LBB0_6
	s_bcnt1_i32_b64 s6, s[6:7]
	v_mov_b32_e32 v1, 0
	v_mov_b32_e32 v2, s6
	global_atomic_add v1, v1, v2, s[4:5] offset:32 sc0

; __global__ void __launch_bounds__(512, 2) mk_fwd(Args a) {
;     ...
;     for (int layer = 0; layer < DEPTH; ++layer) {
;         int tid_ = threadIdx.x, bx_ = blockIdx.x; asm volatile("" : "+v"(tid_)); asm volatile("" : "+s"(bx_));
;         const int tid = tid_, lane = tid & 63, wave = tid >> 6, bx = bx_; (void)tid;
;         const int par = layer & 1;
;         unsigned char* ws = a.ws; asm volatile("" : "+s"(ws));
;         bf16_t* WGLU = (bf16_t*)(ws + WS_WGLU); bf16_t* WOUT = (bf16_t*)(ws + WS_WOUT); bf16_t* W1 = (bf16_t*)(ws + WS_W1); bf16_t* W2 = (bf16_t*)(ws + WS_W2);
;         bf16_t* XN = (bf16_t*)(ws + WS_XN); bf16_t* HID = (bf16_t*)(ws + WS_HID); bf16_t* MIX = (bf16_t*)(ws + WS_MIX); bf16_t* YB = (bf16_t*)(ws + WS_Y); bf16_t* UB = (bf16_t*)(ws + WS_UB);
;         float* PART = (float*)(ws + WS_PART);
;         bf16_t* WIN = (bf16_t*)(ws + (par ? WS_WIN2 : WS_WIN)); bf16_t* WINN = (bf16_t*)(ws + (par ? WS_WIN : WS_WIN2));
;         for (int rp = 0; rp < REP_P1; ++rp) {
;             pg8::Gemm g{XN, WIN, DM, DM, DM, 0, 0}; pg8::StaticOrder S; S.init(NTOK, INW, G, bx);
.LBB0_152:
	v_readlane_b32 vcc_lo, v255, 56
	s_cmp_eq_u32 vcc_lo, 2
	s_cbranch_scc1 .Ldt_nosave
	v_writelane_b32 v255, s13, 55
	v_writelane_b32 v255, s14, 57
	v_writelane_b32 v255, s15, 58
	v_writelane_b32 v255, s20, 59
	v_writelane_b32 v255, s21, 60
	v_writelane_b32 v255, s24, 61
	v_writelane_b32 v255, s25, 62
	v_writelane_b32 v255, s42, 63

; #define PG8_STAGE(bufoff, gbase, voff) do { _Pragma("unroll") for (int _i = 0; _i < 2; ++_i) \
;         __builtin_amdgcn_global_load_lds((const unsigned*)((const char*)(gbase) + (voff)[_i]), (LAS unsigned*)(lds + (bufoff) + ldsw + _i * 8192), 16, 0, 0); } while (0)
;     __device__ __forceinline__ void operator()() const {
;     ...
;         if (tid < 256 * ntab) { const f32x4* p = (const f32x4*)(part + ((size_t)((tid < 256 ? pm0 : pm1) * 256 + (tid & 255))) * 16); const f32x4 a = p[0], b = p[1], c = p[2], d = p[3];
;             const float s = (((a.x + a.y) + (a.z + a.w)) + ((b.x + b.y) + (b.z + b.w))) + (((c.x + c.y) + (c.z + c.w)) + ((d.x + d.y) + (d.z + d.w))); rsl[tid] = __builtin_amdgcn_rsqf(s * (1.0f / 1024.0f) + 1e-6f); }
; template <class Epi, class Sched, bool ALIGN_EPI = true, bool SP2 = true, class Pre = NoPre>
; __device__ __forceinline__ void gemm_phase(LAS unsigned char* lds, const Gemm g, const Sched& S, const Epi& E, const Pre& pre = Pre()) {
;     ...
;     for (int i = 0; i < 2; ++i) { int R, C; stage_rc(tid * 16 + i * 8192, R, C); const int Rb = Epi::PERM ? ((R & ~31) + perm32(R & 31)) : R;
;         voffA[i] = (unsigned)(R * g.lda + C) * 2u; voffB[i] = (unsigned)(Rb * g.ldb + C) * 2u; }
;     const size_t kstep = (size_t)(BK * 2);
;     const size_t hsA = (size_t)HALF * g.lda * 2, hsB = (size_t)HALF * g.ldb * 2;
;     const unsigned ldsw = (unsigned)wid * 1024u;
;     const int aoff = lds_byte(wr * 64 + fr, fq * 8), boff = lds_byte(wc * 32 + fr, fq * 8);
;     ...
;     Unit cur, nxt; int ui = 0;
;     if (!S.next(0, cur)) return;
;     f32x4 acc[2][2][4][2];
; #pragma unroll
;     for (int a = 0; a < 2; ++a)
; #pragma unroll
;         for (int b = 0; b < 2; ++b)
; #pragma unroll
;             for (int m = 0; m < 4; ++m)
; #pragma unroll
;                 for (int n = 0; n < 2; ++n) acc[a][b][m][n] = (f32x4){0.f, 0.f, 0.f, 0.f};
;     bf16x8 At[4][2], B0[2][2], B1[2][2];
;     const char* cA = PG8_TILE_A(cur); const char* cB = PG8_TILE_B(cur);
;     if constexpr (SP2) {
;         PG8_STAGE(PG8_SB(0, 0), cB, voffB); PG8_STAGE(PG8_SB(0, 1), cB + hsB, voffB); PG8_STAGE(PG8_SA(0, 0), cA, voffA); PG8_STAGE(PG8_SA(0, 1), cA + hsA, voffA);
;         pre();
.LBB0_161:
	v_readlane_b32 s0, v254, 53
	s_and_b32 s15, s0, 1
	s_add_u32 s54, s92, 0x3800000
	s_addc_u32 s55, s93, 0
	s_add_u32 s56, s92, 0x5800000
	s_addc_u32 s57, s93, 0
	s_add_u32 s44, s92, 0x7000000
	s_addc_u32 s45, s93, 0
	s_add_u32 s62, s92, 0xd800000
	s_addc_u32 s63, s93, 0
	s_cmp_eq_u32 s15, 0
	s_cselect_b64 s[64:65], -1, 0
	s_and_b64 vcc, exec, s[38:39]
	s_mov_b32 s18, s42
	v_readlane_b32 s1, v254, 54
	s_cbranch_vccnz .LBB0_307
	v_readlane_b32 vcc_lo, v255, 56
	s_cmp_lg_u32 vcc_lo, 0
	s_cbranch_scc1 .Ldt_cont
	s_cmpk_lt_i32 s49, 128
	s_cbranch_scc1 .Ldt_cont
	s_waitcnt lgkmcnt(0)
	v_writelane_b32 v255, 1, 56
	s_branch .LBB0_307
.Ldt_cont:
	s_waitcnt lgkmcnt(0)
	v_ashrrev_i32_e32 v1, 31, v8
	v_lshrrev_b32_e32 v1, 26, v1
	v_add_u32_e32 v1, v8, v1
	v_ashrrev_i32_e32 v9, 6, v1
	v_bfe_i32 v1, v8, 27, 1
	v_lshlrev_b32_e32 v0, 4, v8
	v_lshrrev_b32_e32 v1, 22, v1
	v_add_u32_e32 v1, v0, v1
	v_and_b32_e32 v1, 0xfffffc00, v1
	v_sub_u32_e32 v1, v0, v1
	v_lshrrev_b32_e32 v2, 4, v1
	v_bitop3_b32 v1, v2, v1, 32 bitop3:0x6c
	v_ashrrev_i32_e32 v3, 31, v1
	v_lshrrev_b32_e32 v3, 26, v3
	v_add_u32_e32 v3, v1, v3
	v_lshlrev_b32_e32 v2, 3, v9
	v_ashrrev_i32_e32 v10, 6, v3
	v_and_b32_e32 v3, 0xc0, v3
	v_and_b32_e32 v2, -16, v2
	v_sub_u32_e32 v1, v1, v3
	v_add_u32_e32 v2, v10, v2
	v_ashrrev_i16_sdwa v1, v252, sext(v1) dst_sel:DWORD dst_unused:UNUSED_PAD src0_sel:DWORD src1_sel:BYTE_0
	v_lshlrev_b32_e32 v4, 5, v9
	v_bfe_i32 v11, v1, 0, 16
	v_lshlrev_b32_e32 v1, 1, v2
	v_lshrrev_b32_e32 v3, 2, v2
	v_and_b32_e32 v5, 3, v10
	s_mov_b32 s0, 0x1fffe0
	v_and_b32_e32 v4, 32, v4
	v_and_b32_e32 v1, 24, v1
	v_and_b32_e32 v3, 4, v3
	v_and_or_b32 v5, v2, s0, v5
	v_or3_b32 v1, v5, v3, v1
	v_add_lshl_u32 v3, v4, v11, 1
	v_add_u32_e32 v0, 0x2000, v0
	v_lshl_add_u32 v130, v1, 11, v3
	v_ashrrev_i32_e32 v1, 31, v0
	v_lshrrev_b32_e32 v1, 22, v1
	v_add_u32_e32 v1, v0, v1
	v_ashrrev_i32_e32 v12, 10, v1
	v_mul_i32_i24_e32 v1, 0x400, v12
	v_sub_u32_e32 v0, v0, v1
	v_lshrrev_b32_e32 v1, 4, v0
	s_ashr_i32 s12, s10, 6
	v_bitop3_b32 v0, v1, v0, 32 bitop3:0x6c
	s_lshl_b32 s27, s12, 10
	v_lshl_add_u32 v128, v2, 11, v3
	v_ashrrev_i32_e32 v2, 31, v0
	s_and_b64 s[8:9], s[64:65], exec
	v_lshrrev_b32_e32 v2, 26, v2
	s_cselect_b32 s8, s6, 0xfc00000
	v_add_u32_e32 v2, v0, v2
	s_add_u32 s58, s92, s8
	v_lshlrev_b32_e32 v1, 3, v12
	v_ashrrev_i32_e32 v13, 6, v2
	v_and_b32_e32 v2, 0xc0, v2
	s_addc_u32 s80, s93, 0
	s_ashr_i32 s29, s28, 31
	s_ashr_i32 s23, s22, 31
	v_and_b32_e32 v1, -16, v1
	v_sub_u32_e32 v0, v0, v2
	s_lshl_b64 s[8:9], s[28:29], 19
	s_lshl_b64 s[16:17], s[22:23], 19
	v_add_u32_e32 v1, v13, v1
	v_ashrrev_i16_sdwa v0, v252, sext(v0) dst_sel:DWORD dst_unused:UNUSED_PAD src0_sel:DWORD src1_sel:BYTE_0
	s_add_u32 s30, s58, s16
	v_lshlrev_b32_e32 v3, 5, v12
	v_bfe_i32 v14, v0, 0, 16
	v_lshlrev_b32_e32 v0, 1, v1
	v_lshrrev_b32_e32 v2, 2, v1
	v_and_b32_e32 v4, 3, v13
	s_addc_u32 s31, s80, s17
	s_add_i32 s81, s27, 0
	v_and_b32_e32 v3, 32, v3
	v_and_b32_e32 v0, 24, v0
	v_and_b32_e32 v2, 4, v2
	v_and_or_b32 v4, v1, s0, v4
	s_add_i32 m0, s81, 0x10000
	v_or3_b32 v0, v4, v2, v0
	v_add_lshl_u32 v2, v3, v14, 1
	global_load_lds_dwordx4 v130, s[30:31]
	s_add_i32 m0, s81, 0x12000
	v_lshl_add_u32 v134, v0, 11, v2
	s_add_u32 s16, s30, 0x40000
	global_load_lds_dwordx4 v134, s[30:31]
	s_addc_u32 s17, s31, 0
	s_add_i32 m0, s81, 0x14000
	v_lshl_add_u32 v132, v1, 11, v2
	global_load_lds_dwordx4 v130, s[16:17]
	s_add_i32 m0, s81, 0x16000
	s_add_u32 s40, s54, s8
	s_addc_u32 s41, s55, s9
	s_add_i32 s82, s81, 0x2000
	global_load_lds_dwordx4 v134, s[16:17]
	s_mov_b32 m0, s81
	s_add_u32 s8, s40, 0x40000
	global_load_lds_dwordx4 v128, s[40:41]
	s_mov_b32 m0, s82
	s_addc_u32 s9, s41, 0
	s_add_i32 s83, s81, 0x4000
	global_load_lds_dwordx4 v132, s[40:41]
	s_mov_b32 m0, s83
	s_add_i32 s84, s81, 0x6000
	global_load_lds_dwordx4 v128, s[8:9]
	s_mov_b32 m0, s84
	s_nop 0
	global_load_lds_dwordx4 v132, s[8:9]
	s_and_saveexec_b64 s[8:9], s[4:5]
	s_cbranch_execz .LBB0_164
	v_readlane_b32 s0, v254, 33
	v_mov_b32_e32 v0, s11
	v_mov_b32_e32 v1, s7
	v_readlane_b32 s1, v254, 34
	s_nop 1
	v_cndmask_b32_e64 v0, v0, v1, s[0:1]
	v_and_b32_e32 v1, 0xff, v236
	v_lshl_or_b32 v0, v0, 8, v1
	v_ashrrev_i32_e32 v1, 31, v0
	v_lshlrev_b64 v[0:1], 6, v[0:1]
	v_lshl_add_u64 v[20:21], s[62:63], 0, v[0:1]
	flat_load_dwordx4 v[0:3], v[20:21]
	flat_load_dwordx4 v[4:7], v[20:21] offset:32
	flat_load_dwordx4 v[16:19], v[20:21] offset:16
	s_nop 0
	flat_load_dwordx4 v[20:23], v[20:21] offset:48
	s_waitcnt vmcnt(0) lgkmcnt(0)
	v_mov_b32_e32 v24, v0
	v_mov_b32_e32 v25, v4
	v_mov_b32_e32 v4, v1
	v_mov_b32_e32 v0, v2
	v_mov_b32_e32 v1, v6
	v_mov_b32_e32 v6, v3
	v_mov_b32_e32 v2, v16
	v_mov_b32_e32 v3, v20
	v_mov_b32_e32 v20, v17
	v_mov_b32_e32 v16, v18
	v_mov_b32_e32 v17, v22
	v_mov_b32_e32 v22, v19
	v_pk_add_f32 v[4:5], v[24:25], v[4:5]
	v_pk_add_f32 v[0:1], v[0:1], v[6:7]
	v_pk_add_f32 v[2:3], v[2:3], v[20:21]
	v_pk_add_f32 v[6:7], v[16:17], v[22:23]
	v_pk_add_f32 v[0:1], v[4:5], v[0:1]
	v_pk_add_f32 v[2:3], v[2:3], v[6:7]
	s_nop 0
	v_pk_add_f32 v[0:1], v[0:1], v[2:3]
	s_nop 0
	v_add_f32_e32 v0, v0, v1
	v_fmamk_f32 v0, v0, 0x3a800000, v239
	v_rsq_f32_e32 v0, v0
	ds_write_b32 v237, v0

; #define LAS __attribute__((address_space(3)))
; template <int MODE  >
; __device__ __forceinline__ void p0_transpose_item(const float* W, int K, int N, const float* gain, bf16_t* WT, LAS float* scr, int item, int lane) {
;     const int nblk = N / 64, kb = item / nblk, nb = item % nblk, k0 = 64 * kb, n0 = 64 * nb;
;     const __amdgpu_buffer_rsrc_t wrs = __builtin_amdgcn_make_buffer_rsrc(WT, 0, N * K * 2, 0x00020000);
;     const int lr = lane >> 4, lc = 4 * (lane & 15);
;     f32x4 v[16];
; #pragma unroll
;     for (int i = 0; i < 16; ++i) v[i] = __builtin_nontemporal_load((const f32x4*)(W + (size_t)(k0 + 4 * i + lr) * N + n0 + lc));
; __global__ void __launch_bounds__(512, 2) mk_fwd(Args a) {
;     ...
;             if (bx >= 64 && rp == 0) {
;                 LAS float* scr = (LAS float*)(lds + wave * 16640);
;                 const int gw = (bx - 64) * 8 + wave, NGW = (G - 64) * 8;
;                 constexpr int I_GLU = (512 / 64) * (1024 / 64), I_OUT = (DM / 64) * (DM / 64), I_1 = (DM / 64) * (FF / 64), I_2 = (FF / 64) * (DM / 64);
;                 for (int it = gw; it < I_GLU + I_OUT + I_1 + I_2; it += NGW) {
;                     int r = it;
;                     if (r < I_GLU) { p0_transpose_item<1>(a.w_glu + (size_t)layer * 512 * 1024, 512, 1024, nullptr, WGLU, scr, r, lane); continue; } r -= I_GLU;
;                     if (r < I_OUT) { p0_transpose_item<0>(a.w_out + (size_t)layer * DM * DM, DM, DM, nullptr, WOUT, scr, r, lane); continue; } r -= I_OUT;
;                     if (r < I_1) { p0_transpose_item<0>(a.w_ff1 + (size_t)layer * DM * FF, DM, FF, a.norm2 + layer * DM, W1, scr, r, lane); continue; } r -= I_1;
.LBB0_307:
	s_add_u32 s4, s92, 0x380000
	s_addc_u32 s0, s93, 0
	v_writelane_b32 v255, s0, 32
	s_add_u32 s0, s92, 0x480000
	s_addc_u32 s1, s93, 0
	v_readlane_b32 s8, v254, 55
	v_readlane_b32 s9, v254, 56
	v_readlane_b32 s10, v254, 57
	v_readlane_b32 s11, v254, 58
	s_add_u32 s8, s92, 0x680000
	v_writelane_b32 v254, s8, 55
	v_writelane_b32 v255, s1, 34
	s_addc_u32 s1, s93, 0
	v_writelane_b32 v254, s9, 56
	v_writelane_b32 v254, s10, 57
	v_writelane_b32 v254, s11, 58
	v_writelane_b32 v255, s1, 35
	s_add_u32 s8, s92, 0xe80000
	v_writelane_b32 v255, s8, 36
	s_addc_u32 s1, s93, 0
	s_sub_i32 s84, s49, 64
	v_writelane_b32 v255, s9, 37
	v_writelane_b32 v255, s10, 38
	v_writelane_b32 v255, s11, 39
	v_readlane_b32 s8, v254, 53
	s_add_i32 s52, s8, 1
	v_readlane_b32 s9, v254, 54
	s_cmp_eq_u32 s8, 3
	v_writelane_b32 v255, s1, 40
	s_mov_b32 s10, s8
	s_cselect_b64 s[8:9], -1, 0
	v_writelane_b32 v255, s8, 41
	s_cmp_lg_u32 s10, 3
	s_mov_b32 s1, 0x1800000
	v_writelane_b32 v255, s9, 42
	s_cselect_b64 s[8:9], -1, 0
	v_writelane_b32 v255, s8, 43
	s_lshr_b32 s58, s84, 3
	s_and_b32 s5, s49, 7
	v_writelane_b32 v255, s9, 44
	s_and_b64 s[8:9], s[64:65], exec
	s_cselect_b32 s96, s1, 0xf400000
	s_brev_b32 s1, 64
	s_cselect_b32 s97, s1, 0xdc00000
	s_lshl_b32 s86, s15, 12
	s_lshl_b32 s8, s10, 6
	s_cmp_eq_u32 s5, 0
	s_cselect_b64 s[46:47], -1, 0
	s_lshl_b32 s82, s5, 2
	v_writelane_b32 v255, s8, 45
	s_add_i32 s82, s82, 4
	s_lshl_b32 s83, s5, 6
	s_lshl_b32 s85, s5, 5
	v_writelane_b32 v255, s9, 46
	v_readlane_b32 vcc_lo, v255, 56
	s_cmp_lg_u32 vcc_lo, 2
	s_cbranch_scc1 .Ldt_b_norm
	v_writelane_b32 v255, 0, 56
	s_branch .Ldt_skipconv
.Ldt_b_norm:
	s_cmp_lt_i32 s49, 64
	s_cbranch_scc1 .LBB0_388
	v_ashrrev_i32_e32 v0, 6, v184
	s_movk_i32 s5, 0x4100
	s_waitcnt lgkmcnt(0)
	v_mul_lo_u32 v1, v0, s5
	v_lshl_add_u32 v69, s84, 3, v0
	v_lshlrev_b32_e32 v0, 2, v184
	v_and_b32_e32 v2, 60, v0
	v_lshlrev_b32_e32 v0, 3, v184
	v_and_b32_e32 v91, 56, v0
	v_bfe_u32 v90, v184, 3, 3
	v_add_u32_e32 v1, 0, v1
	v_bfe_u32 v68, v184, 4, 2
	v_mul_u32_u24_e32 v0, 0x104, v91
	v_lshlrev_b32_e32 v3, 2, v90
	s_movk_i32 s5, 0x980
	v_lshl_add_u32 v71, v2, 2, v1
	s_movk_i32 s1, 0x104
	v_add3_u32 v87, v1, v0, v3
	v_or_b32_e32 v0, 4, v68
	v_mov_b32_e32 v1, 0x1450
	v_cmp_gt_i32_e32 vcc, s5, v69
	v_mad_u32_u24 v86, v68, s1, v71
	v_mul_u32_u24_e32 v88, 0x104, v0
	v_mad_u32_u24 v89, v0, s1, v1
	v_lshlrev_b32_e32 v72, 2, v2
	v_lshlrev_b32_e32 v70, 6, v69
	s_and_saveexec_b64 s[20:21], vcc
	s_cbranch_execz .LBB0_355
	v_readlane_b32 s8, v254, 53
	v_mov_b32_e32 v1, 0x410
	v_mov_b32_e32 v2, 0xc30
	v_readlane_b32 s9, v254, 54
	v_mad_u32_u24 v1, v0, s1, v1
	v_mad_u32_u24 v0, v0, s1, v2
	s_mov_b32 s16, s8
	s_lshl_b32 s8, s8, 22
	s_mov_b32 s9, s59
	s_mov_b32 s1, s36
	s_mov_b32 s3, s37
	v_readlane_b32 s36, v253, 1
	s_lshl_b64 s[8:9], s[8:9], 2
	v_readlane_b32 s40, v253, 5
	v_readlane_b32 s12, v255, 36
	v_readlane_b32 s41, v253, 6
	s_add_u32 s10, s40, s8
	v_readlane_b32 s13, v255, 37
	v_readlane_b32 s5, v255, 40
	v_readlane_b32 s38, v253, 3
	s_addc_u32 s11, s41, s9
	v_readlane_b32 s14, v255, 38
	v_readlane_b32 s15, v255, 39
	s_and_b32 s13, s5, 0xffff
	v_readlane_b32 s39, v253, 4
	v_mov_b32_e32 v73, v201
	v_writelane_b32 v255, s12, 36
	s_add_u32 s8, s38, s8
	v_lshl_add_u64 v[74:75], s[10:11], 0, v[72:73]
	v_writelane_b32 v255, s13, 37
	s_addc_u32 s9, s39, s9
	s_lshl_b32 s10, s16, 10
	s_mov_b32 s11, s59
	v_writelane_b32 v255, s14, 38
	s_lshl_b64 s[10:11], s[10:11], 2
	v_readlane_b32 s37, v253, 2
	v_writelane_b32 v255, s15, 39
	v_readlane_b32 s12, v254, 55
	s_add_u32 s24, s36, s10
	v_readlane_b32 s13, v254, 56
	s_mov_b32 s36, s1
	s_addc_u32 s25, s37, s11
	v_lshl_add_u64 v[76:77], s[8:9], 0, v[72:73]
	v_readlane_b32 s1, v255, 35
	s_lshl_b32 s8, s16, 20
	s_mov_b32 s9, s59
	s_mov_b64 s[10:11], s[64:65]
	v_readlane_b32 s64, v253, 25
	s_and_b32 s13, s1, 0xffff
	s_lshl_b64 s[8:9], s[8:9], 2
	v_readlane_b32 s78, v253, 39
	v_readlane_b32 s79, v253, 40
	s_add_u32 s8, s78, s8
	v_readlane_b32 s15, v254, 58
	s_addc_u32 s9, s79, s9
	v_readlane_b32 s14, v254, 57
	s_mov_b32 s15, s95
	v_lshl_add_u64 v[78:79], s[8:9], 0, v[72:73]
	v_readlane_b32 s1, v255, 34
	s_lshl_b32 s8, s16, 19
	s_mov_b32 s9, s59
	v_writelane_b32 v254, s12, 55
	v_readlane_b32 s76, v253, 37
	s_and_b32 s1, s1, 0xffff
	s_lshl_b64 s[8:9], s[8:9], 2
	v_writelane_b32 v254, s13, 56
	v_readlane_b32 s77, v253, 38
	s_add_u32 s8, s76, s8
	v_readlane_b32 s42, v253, 7
	s_mov_b32 s37, s3
	v_writelane_b32 v254, s14, 57
	v_readlane_b32 s65, v253, 26
	s_addc_u32 s9, s77, s9
	v_readlane_b32 s5, v255, 32
	v_lshlrev_b32_e32 v2, 10, v90
	s_mov_b32 s42, s18
	v_or_b32_e32 v92, 8, v90
	v_or_b32_e32 v93, 16, v90
	v_or_b32_e32 v94, 24, v90
	v_or_b32_e32 v95, 32, v90
	v_or_b32_e32 v96, 40, v90
	v_or_b32_e32 v97, 48, v90
	v_or_b32_e32 v98, 56, v90
	v_writelane_b32 v254, s15, 58
	s_mov_b64 s[64:65], s[10:11]
	s_mov_b32 s3, s95
	v_lshl_add_u64 v[80:81], s[8:9], 0, v[72:73]
	s_mov_b32 s7, s95
	s_and_b32 s5, s5, 0xffff
	v_lshl_or_b32 v73, v69, 16, v2
	s_lshl_b32 s8, s37, 16
	v_lshlrev_b32_e32 v99, 6, v69
	s_lshl_b32 s9, s37, 6
	v_lshlrev_b32_e32 v100, 2, v69
	s_lshl_b32 s16, s37, 2
	s_mov_b64 s[28:29], 0
	v_add_u32_e32 v101, v71, v1
	v_add_u32_e32 v102, v71, v0
	v_mov_b32_e32 v103, v69
	v_readlane_b32 s43, v253, 8
	v_readlane_b32 s66, v253, 27
	v_readlane_b32 s67, v253, 28
	v_readlane_b32 s68, v253, 29
	v_readlane_b32 s69, v253, 30
	v_readlane_b32 s70, v253, 31
	v_readlane_b32 s71, v253, 32
	v_readlane_b32 s72, v253, 33
	v_readlane_b32 s73, v253, 34
	v_readlane_b32 s74, v253, 35
	v_readlane_b32 s75, v253, 36
	s_branch .LBB0_311

; __device__ __forceinline__ void ssm_gen(LAS unsigned char* lds, const Args& a, int layer, int g, int j8) {
;     ...
;     if (tid < 16) DSK[tid] = a.d_skip[layer * 512 + g * 16 + tid];
; __global__ void __launch_bounds__(512, 2) mk_fwd(Args a) {
;     ...
;                 __syncthreads(); ssm_gen(lds, a, layer, (bx - 64) >> 3, (bx - 64) & 7);
.Ldt_skipconv:
	v_mov_b32_e32 v12, v236
	s_waitcnt vmcnt(0) lgkmcnt(0)
	s_barrier
	v_readlane_b32 vcc_lo, v255, 56
	s_cmp_lg_u32 vcc_lo, 1
	s_cbranch_scc1 .Ldt_c_norm
	v_writelane_b32 v255, 2, 56
	v_readlane_b32 s13, v255, 55
	v_readlane_b32 s14, v255, 57
	v_readlane_b32 s15, v255, 58
	v_readlane_b32 s20, v255, 59
	v_readlane_b32 s21, v255, 60
	v_readlane_b32 s24, v255, 61
	v_readlane_b32 s25, v255, 62
	v_readlane_b32 s42, v255, 63
	s_nop 3
	s_branch .LBB0_152
.Ldt_c_norm:
	s_nop 0
	v_cmp_gt_i32_e32 vcc, 16, v12
	s_and_saveexec_b64 s[10:11], vcc
	s_cbranch_execz .LBB0_360
	v_readlane_b32 s8, v254, 53
	s_lshl_b32 s5, s58, 4
	s_lshl_b32 s7, s8, 9
	s_add_i32 s5, s5, s7
	v_add_u32_e32 v0, s5, v12
	v_readlane_b32 s12, v253, 25
	v_ashrrev_i32_e32 v1, 31, v0
	v_readlane_b32 s22, v253, 35
	v_readlane_b32 s23, v253, 36
	v_readlane_b32 s9, v254, 54
	v_readlane_b32 s13, v253, 26
	v_lshl_add_u64 v[0:1], v[0:1], 2, s[22:23]
	global_load_dword v0, v[0:1], off
	v_lshl_add_u32 v1, v12, 2, 0
	v_add_u32_e32 v1, 0x20800, v1
	v_readlane_b32 s14, v253, 27
	v_readlane_b32 s15, v253, 28
	v_readlane_b32 s16, v253, 29
	v_readlane_b32 s17, v253, 30
	v_readlane_b32 s18, v253, 31
	v_readlane_b32 s19, v253, 32
	v_readlane_b32 s20, v253, 33
	v_readlane_b32 s21, v253, 34
	v_readlane_b32 s24, v253, 37
	v_readlane_b32 s25, v253, 38
	v_readlane_b32 s26, v253, 39
	v_readlane_b32 s27, v253, 40
	s_waitcnt vmcnt(0)
	ds_write_b32 v1, v0
